# attention loop VALU front-loaded (25 cycles of VALU per MFMA slot, last slots lighter)
# baseline (speedup 1.0000x reference)
.Lattn_h0_nok1:
	s_or_b64 exec, exec, s[8:9]
	v_lshl_add_u64 v[182:183], v[164:165], 0, s[90:91]
	global_load_dwordx4 v[154:157], v[182:183], off
	s_setprio 1
	s_add_i32 s15, s13, 0
	s_add_i32 s14, s10, 0
	s_add_i32 s16, s11, 0
	v_add3_u32 v177, s15, v174, v112
	v_add3_u32 v178, s14, v176, v112
	ds_read_b128 v[202:205], v177
	ds_read_b128 v[206:209], v177 offset:6656
	ds_read_b128 v[210:213], v177 offset:32
	v_mfma_f32_32x32x16_bf16 v[16:31], v[194:197], v[214:217], v[16:31]
	ds_read_b128 v[194:197], v177 offset:6688
	v_exp_f32_e32 v64, v64
	v_exp_f32_e32 v65, v65
	v_exp_f32_e32 v66, v66
	v_exp_f32_e32 v67, v67
	v_mfma_f32_32x32x16_bf16 v[0:15], v[198:201], v[214:217], v[0:15]
	ds_read_b128 v[198:201], v177 offset:64
	v_exp_f32_e32 v68, v68
	v_exp_f32_e32 v69, v69
	v_exp_f32_e32 v70, v70
	s_waitcnt lgkmcnt(4)
	v_mfma_f32_32x32x16_bf16 v[96:111], v[202:205], v[126:129], v[32:47]
	ds_read_b128 v[202:205], v177 offset:6720
	v_exp_f32_e32 v71, v71
	v_exp_f32_e32 v72, v72
	v_add_f32_e32 v179, v179, v64
	s_waitcnt lgkmcnt(4)
	v_mfma_f32_32x32x16_bf16 v[80:95], v[206:209], v[126:129], v[32:47]
	ds_read_b128 v[206:209], v177 offset:96
	v_exp_f32_e32 v73, v73
	v_add_f32_e32 v218, v218, v65
	v_exp_f32_e32 v74, v74
	v_add_f32_e32 v179, v179, v66
	s_waitcnt lgkmcnt(4)
	v_mfma_f32_32x32x16_bf16 v[96:111], v[210:213], v[130:133], v[96:111]
	ds_read_b128 v[210:213], v177 offset:6752
	v_exp_f32_e32 v75, v75
	v_add_f32_e32 v218, v218, v67
	v_exp_f32_e32 v76, v76
	v_add_f32_e32 v179, v179, v68
	v_exp_f32_e32 v77, v77
	s_waitcnt lgkmcnt(4)
	v_mfma_f32_32x32x16_bf16 v[80:95], v[194:197], v[130:133], v[80:95]
	ds_read_b128 v[194:197], v177 offset:128
	v_add_f32_e32 v218, v218, v69
	v_exp_f32_e32 v78, v78
	v_add_f32_e32 v179, v179, v70
	v_exp_f32_e32 v79, v79
	s_waitcnt lgkmcnt(4)
	v_mfma_f32_32x32x16_bf16 v[96:111], v[198:201], v[134:137], v[96:111]
	ds_read_b128 v[198:201], v177 offset:6784
	v_add_f32_e32 v218, v218, v71
	v_cvt_pk_bf16_f32 v64, v64, v65
	v_cvt_pk_bf16_f32 v65, v66, v67
	v_cvt_pk_bf16_f32 v66, v68, v69
	v_cvt_pk_bf16_f32 v67, v70, v71
	s_waitcnt lgkmcnt(4)
	v_mfma_f32_32x32x16_bf16 v[80:95], v[202:205], v[134:137], v[80:95]
	ds_read_b128 v[202:205], v177 offset:160
	v_exp_f32_e32 v48, v48
	v_add_f32_e32 v179, v179, v72
	v_exp_f32_e32 v49, v49
	v_add_f32_e32 v218, v218, v73
	s_waitcnt lgkmcnt(4)
	v_mfma_f32_32x32x16_bf16 v[96:111], v[206:209], v[138:141], v[96:111]
	ds_read_b128 v[206:209], v177 offset:6816
	v_exp_f32_e32 v50, v50
	v_add_f32_e32 v179, v179, v74
	v_exp_f32_e32 v51, v51
	v_add_f32_e32 v218, v218, v75
	v_exp_f32_e32 v52, v52
	v_add_u32_e32 v180, s16, v170
	s_waitcnt vmcnt(3)
	ds_write_b128 v180, v[122:125]
	s_and_saveexec_b64 s[6:7], s[4:5]
	v_add_u32_e32 v180, s16, v173
	ds_write_b128 v180, v[118:121]
	s_or_b64 exec, exec, s[6:7]
	v_add_u32_e32 v180, s16, v172
	v_add_u32_e32 v180, 0x3000, v180
	s_waitcnt vmcnt(2)
	ds_write2_b64 v180, v[150:151], v[152:153] offset0:128 offset1:130
	s_waitcnt lgkmcnt(6)
	v_mfma_f32_32x32x16_bf16 v[80:95], v[210:213], v[138:141], v[80:95]
	ds_read_b128 v[210:213], v178 offset:13312
	v_add_f32_e32 v179, v179, v76
	v_exp_f32_e32 v53, v53
	v_add_f32_e32 v218, v218, v77
	v_exp_f32_e32 v54, v54
	s_waitcnt lgkmcnt(6)
	v_mfma_f32_32x32x16_bf16 v[96:111], v[194:197], v[142:145], v[96:111]
	ds_read_b128 v[194:197], v178 offset:17920
	v_add_f32_e32 v179, v179, v78
	v_exp_f32_e32 v55, v55
	v_add_f32_e32 v218, v218, v79
	v_cvt_pk_bf16_f32 v72, v72, v73
	s_waitcnt lgkmcnt(6)
	v_mfma_f32_32x32x16_bf16 v[80:95], v[198:201], v[142:145], v[80:95]
	ds_read_b128 v[198:201], v178 offset:13344
	v_cvt_pk_bf16_f32 v73, v74, v75
	v_cvt_pk_bf16_f32 v74, v76, v77
	v_cvt_pk_bf16_f32 v75, v78, v79
	v_add_f32_e32 v179, v179, v48
	v_add_f32_e32 v218, v218, v49
	v_add_f32_e32 v179, v179, v50
	s_waitcnt lgkmcnt(6)
	v_mfma_f32_32x32x16_bf16 v[96:111], v[202:205], v[146:149], v[96:111]
	ds_read_b128 v[202:205], v178 offset:17952
	v_add_f32_e32 v218, v218, v51
	v_add_f32_e32 v179, v179, v52
	v_add_f32_e32 v218, v218, v53
	v_add_f32_e32 v179, v179, v54
	v_add_f32_e32 v218, v218, v55
	v_cvt_pk_bf16_f32 v48, v48, v49
	v_cvt_pk_bf16_f32 v49, v50, v51
	s_waitcnt lgkmcnt(6)
	v_mfma_f32_32x32x16_bf16 v[80:95], v[206:209], v[146:149], v[80:95]
	ds_read_b128 v[206:209], v178 offset:13376
	v_cvt_pk_bf16_f32 v50, v52, v53
	v_cvt_pk_bf16_f32 v51, v54, v55
	v_exp_f32_e32 v56, v56
	v_exp_f32_e32 v57, v57
	s_waitcnt lgkmcnt(4)
	v_mfma_f32_32x32x16_bf16 v[16:31], v[210:213], v[64:67], v[16:31]
	ds_read_b128 v[210:213], v178 offset:17984
	v_exp_f32_e32 v58, v58
	v_exp_f32_e32 v59, v59
	v_exp_f32_e32 v60, v60
	s_waitcnt lgkmcnt(4)
	v_mfma_f32_32x32x16_bf16 v[0:15], v[194:197], v[64:67], v[0:15]
	ds_read_b128 v[194:197], v178 offset:13408
	v_exp_f32_e32 v61, v61
	v_exp_f32_e32 v62, v62
	v_exp_f32_e32 v63, v63
	s_waitcnt lgkmcnt(4)
	v_mfma_f32_32x32x16_bf16 v[16:31], v[198:201], v[72:75], v[16:31]
	ds_read_b128 v[198:201], v178 offset:18016
	v_add_f32_e32 v179, v179, v56
	v_add_f32_e32 v218, v218, v57
	v_add_f32_e32 v179, v179, v58
	v_add_f32_e32 v218, v218, v59
	v_add_f32_e32 v179, v179, v60
	v_add_f32_e32 v218, v218, v61
	v_add_f32_e32 v179, v179, v62
	s_waitcnt lgkmcnt(4)
	v_mfma_f32_32x32x16_bf16 v[0:15], v[202:205], v[72:75], v[0:15]
	v_add_f32_e32 v218, v218, v63
	v_cvt_pk_bf16_f32 v214, v56, v57
	v_cvt_pk_bf16_f32 v215, v58, v59
	v_cvt_pk_bf16_f32 v216, v60, v61
	v_cvt_pk_bf16_f32 v217, v62, v63
	s_waitcnt lgkmcnt(3)
	v_mfma_f32_32x32x16_bf16 v[16:31], v[206:209], v[48:51], v[16:31]
	s_waitcnt lgkmcnt(2)
	v_mfma_f32_32x32x16_bf16 v[0:15], v[210:213], v[48:51], v[0:15]
	s_setprio 0
	s_waitcnt lgkmcnt(0)
	s_barrier
	s_min_u32 s17, s12, 0xfb
	s_add_i32 s17, s17, 4
	s_mul_i32 s3, s17, 0x3000
	s_add_u32 s6, s42, s3
	s_addc_u32 s7, s43, 0
	s_lshl_b32 s90, s17, 13
	v_lshl_add_u64 v[182:183], v[162:163], 1, s[6:7]
	global_load_dwordx4 v[122:125], v[182:183], off
	s_and_saveexec_b64 s[8:9], s[4:5]
	s_cbranch_execz .Lattn_h1_nok1
	v_lshl_add_u64 v[182:183], s[6:7], 0, v[168:169]
	global_load_dwordx4 v[118:121], v[182:183], off
.Lattn_h1_nok1:
	s_or_b64 exec, exec, s[8:9]
	v_lshl_add_u64 v[182:183], v[164:165], 0, s[90:91]
	global_load_dwordx4 v[150:153], v[182:183], off
	s_setprio 1
	v_add3_u32 v177, s16, v174, v112
	v_add3_u32 v178, s15, v176, v112
	ds_read_b128 v[202:205], v177
	ds_read_b128 v[206:209], v177 offset:6656
	ds_read_b128 v[210:213], v177 offset:32
	v_mfma_f32_32x32x16_bf16 v[16:31], v[194:197], v[214:217], v[16:31]
	ds_read_b128 v[194:197], v177 offset:6688
	v_exp_f32_e32 v96, v96
	v_exp_f32_e32 v97, v97
	v_exp_f32_e32 v98, v98
	v_exp_f32_e32 v99, v99
	v_mfma_f32_32x32x16_bf16 v[0:15], v[198:201], v[214:217], v[0:15]
	ds_read_b128 v[198:201], v177 offset:64
	v_exp_f32_e32 v100, v100
	v_exp_f32_e32 v101, v101
	v_exp_f32_e32 v102, v102
	s_waitcnt lgkmcnt(4)
	v_mfma_f32_32x32x16_bf16 v[64:79], v[202:205], v[126:129], v[32:47]
	ds_read_b128 v[202:205], v177 offset:6720
	v_exp_f32_e32 v103, v103
	v_exp_f32_e32 v104, v104
	v_add_f32_e32 v179, v179, v96
	s_waitcnt lgkmcnt(4)
	v_mfma_f32_32x32x16_bf16 v[48:63], v[206:209], v[126:129], v[32:47]
	ds_read_b128 v[206:209], v177 offset:96
	v_exp_f32_e32 v105, v105
	v_add_f32_e32 v218, v218, v97
	v_exp_f32_e32 v106, v106
	v_add_f32_e32 v179, v179, v98
	s_waitcnt lgkmcnt(4)
	v_mfma_f32_32x32x16_bf16 v[64:79], v[210:213], v[130:133], v[64:79]
	ds_read_b128 v[210:213], v177 offset:6752
	v_exp_f32_e32 v107, v107
	v_add_f32_e32 v218, v218, v99
	v_exp_f32_e32 v108, v108
	v_add_f32_e32 v179, v179, v100
	v_exp_f32_e32 v109, v109
	s_waitcnt lgkmcnt(4)
	v_mfma_f32_32x32x16_bf16 v[48:63], v[194:197], v[130:133], v[48:63]
	ds_read_b128 v[194:197], v177 offset:128
	v_add_f32_e32 v218, v218, v101
	v_exp_f32_e32 v110, v110
	v_add_f32_e32 v179, v179, v102
	v_exp_f32_e32 v111, v111
	s_waitcnt lgkmcnt(4)
	v_mfma_f32_32x32x16_bf16 v[64:79], v[198:201], v[134:137], v[64:79]
	ds_read_b128 v[198:201], v177 offset:6784
	v_add_f32_e32 v218, v218, v103
	v_cvt_pk_bf16_f32 v96, v96, v97
	v_cvt_pk_bf16_f32 v97, v98, v99
	v_cvt_pk_bf16_f32 v98, v100, v101
	v_cvt_pk_bf16_f32 v99, v102, v103
	s_waitcnt lgkmcnt(4)
	v_mfma_f32_32x32x16_bf16 v[48:63], v[202:205], v[134:137], v[48:63]
	ds_read_b128 v[202:205], v177 offset:160
	v_exp_f32_e32 v80, v80
	v_add_f32_e32 v179, v179, v104
	v_exp_f32_e32 v81, v81
	v_add_f32_e32 v218, v218, v105
	s_waitcnt lgkmcnt(4)
	v_mfma_f32_32x32x16_bf16 v[64:79], v[206:209], v[138:141], v[64:79]
	ds_read_b128 v[206:209], v177 offset:6816
	v_exp_f32_e32 v82, v82
	v_add_f32_e32 v179, v179, v106
	v_exp_f32_e32 v83, v83
	v_add_f32_e32 v218, v218, v107
	v_exp_f32_e32 v84, v84
	v_add_u32_e32 v180, s14, v170
	s_waitcnt vmcnt(3)
	ds_write_b128 v180, v[158:161]
	s_and_saveexec_b64 s[6:7], s[4:5]
	v_add_u32_e32 v180, s14, v173
	ds_write_b128 v180, v[114:117]
	s_or_b64 exec, exec, s[6:7]
	v_add_u32_e32 v180, s14, v172
	v_add_u32_e32 v180, 0x3000, v180
	s_waitcnt vmcnt(2)
	ds_write2_b64 v180, v[154:155], v[156:157] offset0:128 offset1:130
	s_waitcnt lgkmcnt(6)
	v_mfma_f32_32x32x16_bf16 v[48:63], v[210:213], v[138:141], v[48:63]
	ds_read_b128 v[210:213], v178 offset:13312
	v_add_f32_e32 v179, v179, v108
	v_exp_f32_e32 v85, v85
	v_add_f32_e32 v218, v218, v109
	v_exp_f32_e32 v86, v86
	s_waitcnt lgkmcnt(6)
	v_mfma_f32_32x32x16_bf16 v[64:79], v[194:197], v[142:145], v[64:79]
	ds_read_b128 v[194:197], v178 offset:17920
	v_add_f32_e32 v179, v179, v110
	v_exp_f32_e32 v87, v87
	v_add_f32_e32 v218, v218, v111
	v_cvt_pk_bf16_f32 v104, v104, v105
	s_waitcnt lgkmcnt(6)
	v_mfma_f32_32x32x16_bf16 v[48:63], v[198:201], v[142:145], v[48:63]
	ds_read_b128 v[198:201], v178 offset:13344
	v_cvt_pk_bf16_f32 v105, v106, v107
	v_cvt_pk_bf16_f32 v106, v108, v109
	v_cvt_pk_bf16_f32 v107, v110, v111
	v_add_f32_e32 v179, v179, v80
	v_add_f32_e32 v218, v218, v81
	v_add_f32_e32 v179, v179, v82
	s_waitcnt lgkmcnt(6)
	v_mfma_f32_32x32x16_bf16 v[64:79], v[202:205], v[146:149], v[64:79]
	ds_read_b128 v[202:205], v178 offset:17952
	v_add_f32_e32 v218, v218, v83
	v_add_f32_e32 v179, v179, v84
	v_add_f32_e32 v218, v218, v85
	v_add_f32_e32 v179, v179, v86
	v_add_f32_e32 v218, v218, v87
	v_cvt_pk_bf16_f32 v80, v80, v81
	v_cvt_pk_bf16_f32 v81, v82, v83
	s_waitcnt lgkmcnt(6)
	v_mfma_f32_32x32x16_bf16 v[48:63], v[206:209], v[146:149], v[48:63]
	ds_read_b128 v[206:209], v178 offset:13376
	v_cvt_pk_bf16_f32 v82, v84, v85
	v_cvt_pk_bf16_f32 v83, v86, v87
	v_exp_f32_e32 v88, v88
	v_exp_f32_e32 v89, v89
	s_waitcnt lgkmcnt(4)
	v_mfma_f32_32x32x16_bf16 v[16:31], v[210:213], v[96:99], v[16:31]
	ds_read_b128 v[210:213], v178 offset:17984
	v_exp_f32_e32 v90, v90
	v_exp_f32_e32 v91, v91
	v_exp_f32_e32 v92, v92
	s_waitcnt lgkmcnt(4)
	v_mfma_f32_32x32x16_bf16 v[0:15], v[194:197], v[96:99], v[0:15]
	ds_read_b128 v[194:197], v178 offset:13408
	v_exp_f32_e32 v93, v93
	v_exp_f32_e32 v94, v94
	v_exp_f32_e32 v95, v95
	s_waitcnt lgkmcnt(4)
	v_mfma_f32_32x32x16_bf16 v[16:31], v[198:201], v[104:107], v[16:31]
	ds_read_b128 v[198:201], v178 offset:18016
	v_add_f32_e32 v179, v179, v88
	v_add_f32_e32 v218, v218, v89
	v_add_f32_e32 v179, v179, v90
	v_add_f32_e32 v218, v218, v91
	v_add_f32_e32 v179, v179, v92
	v_add_f32_e32 v218, v218, v93
	v_add_f32_e32 v179, v179, v94
	s_waitcnt lgkmcnt(4)
	v_mfma_f32_32x32x16_bf16 v[0:15], v[202:205], v[104:107], v[0:15]
	v_add_f32_e32 v218, v218, v95
	v_cvt_pk_bf16_f32 v214, v88, v89
	v_cvt_pk_bf16_f32 v215, v90, v91
	v_cvt_pk_bf16_f32 v216, v92, v93
	v_cvt_pk_bf16_f32 v217, v94, v95
	s_waitcnt lgkmcnt(3)
	v_mfma_f32_32x32x16_bf16 v[16:31], v[206:209], v[80:83], v[16:31]
	s_waitcnt lgkmcnt(2)
	v_mfma_f32_32x32x16_bf16 v[0:15], v[210:213], v[80:83], v[0:15]
	s_setprio 0
	s_cmpk_lt_u32 s12, 0xfe
	s_waitcnt lgkmcnt(0)
	s_barrier
	s_cbranch_scc0 .Lattn_exit
	s_mov_b32 s6, s11
	s_mov_b32 s11, s13
	s_branch .LBB0_1048
